# neighbourhood attention: score copies moved off the bias path; differential attention: row-sum overflow test branches on vcc directly
# baseline (speedup 1.0000x reference)
; #define LAS __attribute__((address_space(3)))
; #define MFMA32(a, b, c) __builtin_amdgcn_mfma_f32_32x32x16_bf16((a), (b), (c), 0, 0, 0)
; template <int MODE>
; __device__ __forceinline__ void attn_item(PK p, int l, LAS unsigned char* lds, int b, int h, int qb, bool ctxq, float lam, float lam_init) {
;     ...
;         bool active = true; int krow = 0;
;         if (nabias && t < nloc) { krow = loc0 + t; active = (krow >= sw) && (krow < sw + 8); }
;         bool slow = (MODE == 0) || (t == 0);
;         if (active) {
;           again:
;             LAS unsigned char* Kb = lds + cbuf * BUFSZ + koff;
;             f32x16 S[NCOMP][2];
; #pragma unroll
;             for (int c = 0; c < NCOMP; ++c)
; #pragma unroll
;                 for (int kt = 0; kt < 2; ++kt) {
;                     bf16x8 kf[NKS];
; #pragma unroll
;                     for (int ks = 0; ks < NKS; ++ks) kf[ks] = *(const LAS bf16x8*)(Kb + kt * 32 * KSTR + (c * NKS + ks) * 32);
; #pragma unroll
;                     for (int r = 0; r < 16; ++r) S[c][kt][r] = 0.f;
;                     __builtin_amdgcn_s_setprio(1);
; #pragma unroll
;                     for (int ks = 0; ks < NKS; ++ks) S[c][kt] = MFMA32(kf[ks], qf[c * NKS + ks], S[c][kt]);
;                     __builtin_amdgcn_s_setprio(0);
;                 }
.LBB0_144:
	s_cmp_ge_i32 s10, s6
	s_cselect_b64 s[0:1], -1, 0
	s_cmp_lt_i32 s10, s6
	s_mov_b32 s12, s94
	s_cselect_b64 s[94:95], -1, 0
	s_add_i32 s11, s65, s10
	v_cmp_ge_u32_e32 vcc, s11, v143
	v_cmp_lt_u32_e64 s[40:41], s11, v144
	s_and_b64 s[40:41], vcc, s[40:41]
	s_or_b64 s[62:63], s[0:1], s[40:41]
	s_and_saveexec_b64 s[40:41], s[62:63]
	s_cbranch_execz .LBB0_216
	s_mul_i32 s10, s88, 0x5400
	s_add_i32 s10, s10, 0
	v_add3_u32 v1, s10, v139, v108
	ds_read_b128 v[2:5], v1
	ds_read_b128 v[6:9], v1 offset:32
	ds_read_b128 v[10:13], v1 offset:64
	ds_read_b128 v[66:69], v1 offset:96
	s_setprio 1
	s_waitcnt lgkmcnt(3)
	v_mfma_f32_32x32x16_bf16 v[50:65], v[2:5], v[90:93], 0
	s_waitcnt lgkmcnt(2)
	v_mfma_f32_32x32x16_bf16 v[50:65], v[6:9], v[94:97], v[50:65]
	s_waitcnt lgkmcnt(1)
	v_mfma_f32_32x32x16_bf16 v[50:65], v[10:13], v[98:101], v[50:65]
	s_waitcnt lgkmcnt(0)
	v_mfma_f32_32x32x16_bf16 v[50:65], v[66:69], v[102:105], v[50:65]
	s_setprio 0
	ds_read_b128 v[2:5], v1 offset:4608
	ds_read_b128 v[6:9], v1 offset:4640
	ds_read_b128 v[10:13], v1 offset:4672
	ds_read_b128 v[120:123], v1 offset:4704
	s_setprio 1
	s_waitcnt lgkmcnt(3)
	v_mfma_f32_32x32x16_bf16 v[66:81], v[2:5], v[90:93], 0
	s_waitcnt lgkmcnt(2)
	v_mfma_f32_32x32x16_bf16 v[66:81], v[6:9], v[94:97], v[66:81]
	s_waitcnt lgkmcnt(1)
	v_mfma_f32_32x32x16_bf16 v[66:81], v[10:13], v[98:101], v[66:81]
	s_waitcnt lgkmcnt(0)
	v_mfma_f32_32x32x16_bf16 v[66:81], v[120:123], v[102:105], v[66:81]
	s_setprio 0
	s_mov_b64 s[62:63], -1
	s_andn2_b64 vcc, exec, s[94:95]
	s_nop 8
	s_cbranch_vccnz .LBB0_211
; #define LAS __attribute__((address_space(3)))
; template <int MODE>
; __device__ __forceinline__ void attn_item(PK p, int l, LAS unsigned char* lds, int b, int h, int qb, bool ctxq, float lam, float lam_init) {
;     ...
; #pragma unroll
;             for (int c = 0; c < NCOMP; ++c) {
;                 float mx = -1e30f;
;                 if (nabias && t < nloc) {
;                     const LAS float* bt = (const LAS float*)(lds + BIAS_OFF) + (krow - rw + 7) * 31;
; #pragma unroll
;                     for (int kt = 0; kt < 2; ++kt)
; #pragma unroll
;                         for (int r = 0; r < 16; ++r) { const int jk = 32 * kt + (r & 3) + 8 * (r >> 2) + 4 * g; const bool ok = (jk >= cst) && (jk < cst + 16);
;                             const float bv = bt[clampi(jk - jq + 15, 0, 30)]; const float xv = ok ? (S[c][kt][r] + bv) : -1e30f; S[c][kt][r] = xv; mx = fmaxf(mx, xv); }
;                 } else {
; #pragma unroll
;                     for (int kt = 0; kt < 2; ++kt)
; #pragma unroll
;                         for (int r = 0; r < 16; r += 2) mx = fmaxf(fmaxf(mx, S[c][kt][r]), S[c][kt][r + 1]);
;                 }
;                 mxc[c] = mx;
	s_and_b64 s[0:1], s[0:1], exec
	s_cselect_b32 s0, 0, s11
	v_sub_u32_e32 v1, s0, v142
	s_movk_i32 s0, 0x7c
	v_mul_lo_u32 v1, v1, s0
	v_add_u32_e32 v1, 0, v1
	v_mov_b32_e32 v3, 0xf149f2ca
	v_mov_b32_e32 v2, 0xf149f2ca
	v_mov_b32_e32 v218, 0xf149f2ca
	v_lshl_add_u32 v2, v145, 2, v1
	v_lshl_add_u32 v3, v146, 2, v1
	v_lshl_add_u32 v4, v147, 2, v1
	v_lshl_add_u32 v5, v148, 2, v1
	v_lshl_add_u32 v6, v149, 2, v1
	v_lshl_add_u32 v7, v150, 2, v1
	v_lshl_add_u32 v8, v151, 2, v1
	v_lshl_add_u32 v9, v152, 2, v1
	v_lshl_add_u32 v10, v153, 2, v1
	v_lshl_add_u32 v11, v154, 2, v1
	v_lshl_add_u32 v12, v155, 2, v1
	v_lshl_add_u32 v13, v156, 2, v1
	v_lshl_add_u32 v14, v157, 2, v1
	v_lshl_add_u32 v15, v158, 2, v1
	v_lshl_add_u32 v120, v159, 2, v1
	v_lshl_add_u32 v121, v160, 2, v1
	v_lshl_add_u32 v122, v161, 2, v1
	v_lshl_add_u32 v123, v162, 2, v1
	v_lshl_add_u32 v124, v163, 2, v1
	v_lshl_add_u32 v125, v164, 2, v1
	v_lshl_add_u32 v126, v165, 2, v1
	v_lshl_add_u32 v127, v166, 2, v1
	v_lshl_add_u32 v128, v167, 2, v1
	v_lshl_add_u32 v129, v168, 2, v1
	v_lshl_add_u32 v130, v169, 2, v1
	v_lshl_add_u32 v131, v170, 2, v1
	v_lshl_add_u32 v132, v171, 2, v1
	v_lshl_add_u32 v133, v172, 2, v1
	v_lshl_add_u32 v134, v173, 2, v1
	v_lshl_add_u32 v135, v174, 2, v1
	v_lshl_add_u32 v136, v175, 2, v1
	v_lshl_add_u32 v137, v176, 2, v1
	ds_read_b32 v2, v2 offset:65440
	ds_read_b32 v3, v3 offset:65380
	ds_read_b32 v4, v4 offset:65380
	ds_read_b32 v5, v5 offset:65380
	ds_read_b32 v6, v6 offset:65380
	ds_read_b32 v7, v7 offset:65380
	ds_read_b32 v8, v8 offset:65380
	ds_read_b32 v9, v9 offset:65380
	ds_read_b32 v10, v10 offset:65380
	ds_read_b32 v11, v11 offset:65380
	ds_read_b32 v12, v12 offset:65380
	ds_read_b32 v13, v13 offset:65380
	s_waitcnt lgkmcnt(0)
	ds_read_b32 v14, v14 offset:65380
	ds_read_b32 v15, v15 offset:65380
	ds_read_b32 v120, v120 offset:65380
	ds_read_b32 v121, v121 offset:65380
	ds_read_b32 v122, v122 offset:65380
	ds_read_b32 v123, v123 offset:65380
	ds_read_b32 v124, v124 offset:65380
	ds_read_b32 v125, v125 offset:65380
	ds_read_b32 v126, v126 offset:65380
	ds_read_b32 v127, v127 offset:65380
	ds_read_b32 v128, v128 offset:65380
	ds_read_b32 v129, v129 offset:65380
	v_add_f32_e32 v2, v50, v2
	v_add_f32_e32 v3, v51, v3
	v_add_f32_e32 v4, v52, v4
	v_add_f32_e32 v5, v53, v5
	v_add_f32_e32 v6, v54, v6
	v_add_f32_e32 v7, v55, v7
	v_add_f32_e32 v8, v56, v8
	v_add_f32_e32 v9, v57, v9
	v_add_f32_e32 v10, v58, v10
	v_add_f32_e32 v11, v59, v11
	v_add_f32_e32 v12, v60, v12
	v_add_f32_e32 v13, v61, v13
	v_readlane_b32 s62, v255, 31
	v_readlane_b32 s63, v255, 32
	s_nop 1
	v_cndmask_b32_e64 v2, v218, v2, s[62:63]
	v_readlane_b32 s62, v255, 33
	v_readlane_b32 s63, v255, 34
	s_nop 1
	v_cndmask_b32_e64 v3, v218, v3, s[62:63]
	v_readlane_b32 s62, v255, 35
	v_readlane_b32 s63, v255, 36
	s_nop 1
	v_cndmask_b32_e64 v4, v218, v4, s[62:63]
	v_readlane_b32 s62, v255, 37
	v_readlane_b32 s63, v255, 38
	s_nop 1
	v_cndmask_b32_e64 v5, v218, v5, s[62:63]
	v_readlane_b32 s62, v255, 39
	v_readlane_b32 s63, v255, 40
	s_nop 1
	v_cndmask_b32_e64 v6, v218, v6, s[62:63]
	v_cndmask_b32_e64 v7, v218, v7, s[14:15]
	v_cndmask_b32_e64 v8, v218, v8, s[16:17]
	v_cndmask_b32_e64 v9, v218, v9, s[18:19]
	v_cndmask_b32_e64 v10, v218, v10, s[66:67]
	v_cndmask_b32_e64 v11, v218, v11, s[68:69]
	v_cndmask_b32_e64 v12, v218, v12, s[70:71]
	v_cndmask_b32_e64 v13, v218, v13, s[72:73]
	s_waitcnt lgkmcnt(0)
	ds_read_b32 v130, v130 offset:65380
	ds_read_b32 v131, v131 offset:65380
	ds_read_b32 v132, v132 offset:65380
	ds_read_b32 v133, v133 offset:65380
	ds_read_b32 v134, v134 offset:65380
	ds_read_b32 v135, v135 offset:65380
	ds_read_b32 v136, v136 offset:65380
	ds_read_b32 v137, v137 offset:65380
	v_add_f32_e32 v14, v62, v14
	v_add_f32_e32 v15, v63, v15
	v_add_f32_e32 v120, v64, v120
	v_add_f32_e32 v121, v65, v121
	v_add_f32_e32 v122, v66, v122
	v_add_f32_e32 v123, v67, v123
	v_add_f32_e32 v124, v68, v124
	v_add_f32_e32 v125, v69, v125
	v_add_f32_e32 v126, v70, v126
	v_add_f32_e32 v127, v71, v127
	v_add_f32_e32 v128, v72, v128
	v_add_f32_e32 v129, v73, v129
	v_cndmask_b32_e64 v14, v218, v14, s[74:75]
	v_cndmask_b32_e64 v15, v218, v15, s[76:77]
	v_cndmask_b32_e64 v120, v218, v120, s[78:79]
	v_cndmask_b32_e64 v121, v218, v121, s[80:81]
	v_cndmask_b32_e64 v122, v218, v122, s[58:59]
	v_cndmask_b32_e64 v123, v218, v123, s[42:43]
	v_cndmask_b32_e64 v124, v218, v124, s[60:61]
	v_cndmask_b32_e64 v125, v218, v125, s[2:3]
	v_cndmask_b32_e64 v126, v218, v126, s[84:85]
	v_cndmask_b32_e64 v127, v218, v127, s[38:39]
	v_cndmask_b32_e64 v128, v218, v128, s[46:47]
	v_cndmask_b32_e64 v129, v218, v129, s[48:49]
	s_waitcnt lgkmcnt(0)
	v_add_f32_e32 v130, v74, v130
	v_add_f32_e32 v131, v75, v131
	v_add_f32_e32 v132, v76, v132
	v_add_f32_e32 v133, v77, v133
	v_add_f32_e32 v134, v78, v134
	v_add_f32_e32 v135, v79, v135
	v_add_f32_e32 v136, v80, v136
	v_add_f32_e32 v137, v81, v137
	v_cndmask_b32_e64 v130, v218, v130, s[20:21]
	v_cndmask_b32_e64 v131, v218, v131, s[22:23]
	v_cndmask_b32_e64 v132, v218, v132, s[24:25]
	v_cndmask_b32_e64 v133, v218, v133, s[26:27]
	v_cndmask_b32_e64 v134, v218, v134, s[28:29]
	v_cndmask_b32_e64 v135, v218, v135, s[30:31]
	v_cndmask_b32_e64 v136, v218, v136, s[34:35]
	v_cndmask_b32_e64 v137, v218, v137, s[36:37]
	v_max3_f32 v1, v2, s33, v3
	v_max3_f32 v1, v1, v4, v5
	v_max3_f32 v1, v1, v6, v7
	v_max3_f32 v1, v1, v8, v9
	v_max3_f32 v1, v1, v10, v11
	v_max3_f32 v1, v1, v12, v13
	v_max3_f32 v1, v1, v14, v15
	v_max3_f32 v1, v1, v120, v121
	v_max3_f32 v1, v1, v122, v123
	v_max3_f32 v1, v1, v124, v125
	v_max3_f32 v1, v1, v126, v127
	v_max3_f32 v1, v1, v128, v129
	v_max3_f32 v1, v1, v130, v131
	v_max3_f32 v1, v1, v132, v133
	v_max3_f32 v1, v1, v134, v135
	v_max3_f32 v1, v1, v136, v137
	s_mov_b64 s[62:63], 0
.LBB0_211:
	s_and_b64 vcc, exec, s[62:63]
	s_cbranch_vccz .LBB0_213
	v_mov_b32_e32 v137, v81
	v_mov_b32_e32 v136, v80
	v_mov_b32_e32 v135, v79
	v_mov_b32_e32 v134, v78
	v_mov_b32_e32 v133, v77
	v_mov_b32_e32 v132, v76
	v_mov_b32_e32 v131, v75
	v_mov_b32_e32 v130, v74
	v_mov_b32_e32 v129, v73
	v_mov_b32_e32 v128, v72
	v_mov_b32_e32 v127, v71
	v_mov_b32_e32 v126, v70
	v_mov_b32_e32 v125, v69
	v_mov_b32_e32 v124, v68
	v_mov_b32_e32 v123, v67
	v_mov_b32_e32 v122, v66
	v_mov_b32_e32 v121, v65
	v_mov_b32_e32 v120, v64
	v_mov_b32_e32 v15, v63
	v_mov_b32_e32 v14, v62
	v_mov_b32_e32 v13, v61
	v_mov_b32_e32 v12, v60
	v_mov_b32_e32 v11, v59
	v_mov_b32_e32 v10, v58
	v_mov_b32_e32 v9, v57
	v_mov_b32_e32 v8, v56
	v_mov_b32_e32 v7, v55
	v_mov_b32_e32 v6, v54
	v_mov_b32_e32 v5, v53
	v_mov_b32_e32 v4, v52
	v_mov_b32_e32 v3, v51
	v_mov_b32_e32 v2, v50
	v_max3_f32 v1, v50, s33, v51
	v_max3_f32 v1, v1, v52, v53
	v_max3_f32 v1, v1, v54, v55
	v_max3_f32 v1, v1, v56, v57
	v_max3_f32 v1, v1, v58, v59
	v_max3_f32 v1, v1, v60, v61
	v_max3_f32 v1, v1, v62, v63
	v_max3_f32 v1, v1, v64, v65
	v_max3_f32 v1, v1, v66, v67
	v_max3_f32 v1, v1, v68, v69
	v_max3_f32 v1, v1, v70, v71
	v_max3_f32 v1, v1, v72, v73
	v_max3_f32 v1, v1, v74, v75
	v_max3_f32 v1, v1, v76, v77
	v_max3_f32 v1, v1, v78, v79
	v_max3_f32 v1, v1, v80, v81

; #define LAS __attribute__((address_space(3)))
; __device__ __forceinline__ unsigned cvt_pk_bf16(float lo, float hi) { const f32x2_ v = {lo, hi}; return __builtin_bit_cast(unsigned, __builtin_convertvector(v, bf16x2_)); }
; template <int MODE>
; __device__ __forceinline__ void attn_item(PK p, int l, LAS unsigned char* lds, int b, int h, int qb, bool ctxq, float lam, float lam_init) {
;     ...
;             if (PIPE) {
;                 LAS unsigned char* _vb = lds + pbuf * BUFSZ + KBUF + voff;
;                 f32x2 _rs[NCOMP]; u32x4 _pk[NCOMP][2][2];
; #pragma unroll
;                 for (int c = 0; c < NCOMP; ++c) _rs[c] = (f32x2){0.f, 0.f};
;                 bf16x8 _vf[10];
;     ...
;                 VLOAD_(_vf[0], 0); VLOAD_(_vf[1], 1);
;                 __builtin_amdgcn_sched_barrier(0);
; #pragma unroll
;                 for (int i = 0; i < 17; ++i) {
;                     if (i < 16 && (i & 1) == 0) VLOAD_(_vf[(i >> 1) + 2], (i >> 1) + 2);
;                     if (i < 16) { const int v = i >> 1, c = (NCOMP == 2) ? (i & 1) : 0, kt = v >> 2, s2 = (v >> 1) & 1, dt = v & 1; O[c][dt] = MFMA32(_vf[v], Pold[c][kt][s2], O[c][dt]); }
;                     if (i < 16) {
; #pragma unroll
;                         for (int q2 = 0; q2 < 4; ++q2) { const int idx = 4 * i + q2, c = (idx >> 5) % NCOMP, kt = (idx >> 4) & 1, r = idx & 15; S[c][kt][r] = fast_exp2(S[c][kt][r]); } }
;                     if (i >= 1) {
; #pragma unroll
;                         for (int q2 = 0; q2 < 2; ++q2) { const int j = 2 * (i - 1) + q2, c = (j >> 4) % NCOMP, kt = (j >> 3) & 1, s2 = (j >> 2) & 1, e = j & 3;
;                             const f32x2 ev = (f32x2){S[c][kt][8 * s2 + 2 * e], S[c][kt][8 * s2 + 2 * e + 1]}; _rs[c] += ev; _pk[c][kt][s2][e] = cvt_pk_bf16(ev.x, ev.y); } }
;                     __builtin_amdgcn_sched_barrier(0);
;                 }
;     ...
; #pragma unroll
;                 for (int c = 0; c < NCOMP; ++c) { mxc[c] = _rs[c].x + _rs[c].y;
; #pragma unroll
;                     for (int kt = 0; kt < 2; ++kt)
; #pragma unroll
;                         for (int s2 = 0; s2 < 2; ++s2) P[c][kt][s2] = __builtin_bit_cast(bf16x8, _pk[c][kt][s2]); }
;     ...
;             if (!slow) { bool bad = false;
; #pragma unroll
;                 for (int c = 0; c < NCOMP; ++c) bad = bad || !(mxc[c] < 1.0e18f);
;                 if (__any(bad)) { slow = true;
.LBB0_276:
	s_mul_i32 s0, s19, 0x5400
	v_add_u32_e32 v1, s0, v237
	ds_read_b64_tr_b16 v[190:191], v1 offset:9216
	ds_read_b64_tr_b16 v[192:193], v1 offset:10752
	ds_read_b64_tr_b16 v[196:197], v1 offset:10816
	ds_read_b64_tr_b16 v[194:195], v1 offset:9280
	s_waitcnt lgkmcnt(2)
	v_mfma_f32_32x32x16_bf16 v[52:67], v[190:193], v[176:179], v[52:67]
	ds_read_b64_tr_b16 v[214:215], v1 offset:12288
	ds_read_b64_tr_b16 v[216:217], v1 offset:13824
	v_exp_f32_e32 v116, v116
	v_exp_f32_e32 v117, v117
	v_exp_f32_e32 v118, v118
	v_exp_f32_e32 v119, v119
	v_mfma_f32_32x32x16_bf16 v[36:51], v[190:193], v[184:187], v[36:51]
	v_exp_f32_e32 v120, v120
	v_exp_f32_e32 v121, v121
	v_exp_f32_e32 v122, v122
	v_exp_f32_e32 v123, v123
	v_pk_add_f32 v[2:3], v[116:117], 0 op_sel_hi:[1,0]
	s_nop 0
	v_pk_add_f32 v[2:3], v[118:119], v[2:3]
	s_waitcnt lgkmcnt(2)
	v_mfma_f32_32x32x16_bf16 v[20:35], v[194:197], v[176:179], v[20:35]
	ds_read_b64_tr_b16 v[190:191], v1 offset:12352
	ds_read_b64_tr_b16 v[192:193], v1 offset:13888
	v_exp_f32_e32 v124, v124
	v_exp_f32_e32 v125, v125
	v_exp_f32_e32 v126, v126
	v_exp_f32_e32 v127, v127
	v_pk_add_f32 v[2:3], v[120:121], v[2:3]
	s_nop 0
	v_pk_add_f32 v[2:3], v[122:123], v[2:3]
	v_mfma_f32_32x32x16_bf16 v[4:19], v[194:197], v[184:187], v[4:19]
	v_exp_f32_e32 v128, v128
	v_exp_f32_e32 v129, v129
	v_exp_f32_e32 v130, v130
	v_exp_f32_e32 v131, v131
	v_pk_add_f32 v[2:3], v[124:125], v[2:3]
	s_nop 0
	v_pk_add_f32 v[2:3], v[126:127], v[2:3]
	s_waitcnt lgkmcnt(2)
	v_mfma_f32_32x32x16_bf16 v[52:67], v[214:217], v[172:175], v[52:67]
	ds_read_b64_tr_b16 v[194:195], v1 offset:15360
	ds_read_b64_tr_b16 v[196:197], v1 offset:16896
	v_exp_f32_e32 v100, v100
	v_exp_f32_e32 v101, v101
	v_exp_f32_e32 v102, v102
	v_exp_f32_e32 v103, v103
	v_pk_add_f32 v[2:3], v[128:129], v[2:3]
	s_nop 0
	v_pk_add_f32 v[2:3], v[130:131], v[2:3]
	v_mfma_f32_32x32x16_bf16 v[36:51], v[214:217], v[180:183], v[36:51]
	v_exp_f32_e32 v104, v104
	v_exp_f32_e32 v105, v105
	v_exp_f32_e32 v106, v106
	v_exp_f32_e32 v107, v107
	v_pk_add_f32 v[2:3], v[100:101], v[2:3]
	s_nop 0
	v_pk_add_f32 v[2:3], v[102:103], v[2:3]
	s_waitcnt lgkmcnt(2)
	v_mfma_f32_32x32x16_bf16 v[20:35], v[190:193], v[172:175], v[20:35]
	ds_read_b64_tr_b16 v[214:215], v1 offset:15424
	ds_read_b64_tr_b16 v[216:217], v1 offset:16960
	v_exp_f32_e32 v108, v108
	v_exp_f32_e32 v109, v109
	v_exp_f32_e32 v110, v110
	v_exp_f32_e32 v111, v111
	v_pk_add_f32 v[2:3], v[104:105], v[2:3]
	s_nop 0
	v_pk_add_f32 v[2:3], v[106:107], v[2:3]
	v_mfma_f32_32x32x16_bf16 v[4:19], v[190:193], v[180:183], v[4:19]
	v_exp_f32_e32 v112, v112
	v_exp_f32_e32 v113, v113
	v_exp_f32_e32 v114, v114
	v_exp_f32_e32 v115, v115
	v_pk_add_f32 v[2:3], v[108:109], v[2:3]
	s_nop 0
	v_pk_add_f32 v[2:3], v[110:111], v[2:3]
	s_waitcnt lgkmcnt(2)
	v_mfma_f32_32x32x16_bf16 v[52:67], v[194:197], v[144:147], v[52:67]
	ds_read_b64_tr_b16 v[190:191], v1 offset:18432
	ds_read_b64_tr_b16 v[192:193], v1 offset:19968
	v_exp_f32_e32 v84, v84
	v_exp_f32_e32 v85, v85
	v_exp_f32_e32 v86, v86
	v_exp_f32_e32 v87, v87
	v_pk_add_f32 v[2:3], v[112:113], v[2:3]
	s_nop 0
	v_pk_add_f32 v[2:3], v[114:115], v[2:3]
	v_mfma_f32_32x32x16_bf16 v[36:51], v[194:197], v[164:167], v[36:51]
	v_exp_f32_e32 v88, v88
	v_exp_f32_e32 v89, v89
	v_exp_f32_e32 v90, v90
	v_exp_f32_e32 v91, v91
	v_pk_add_f32 v[194:195], v[84:85], 0 op_sel_hi:[1,0]
	s_nop 0
	v_pk_add_f32 v[198:199], v[86:87], v[194:195]
	s_waitcnt lgkmcnt(2)
	v_mfma_f32_32x32x16_bf16 v[20:35], v[214:217], v[144:147], v[20:35]
	ds_read_b64_tr_b16 v[194:195], v1 offset:18496
	ds_read_b64_tr_b16 v[196:197], v1 offset:20032
	v_exp_f32_e32 v92, v92
	v_exp_f32_e32 v93, v93
	v_exp_f32_e32 v94, v94
	v_exp_f32_e32 v95, v95
	v_pk_add_f32 v[198:199], v[88:89], v[198:199]
	s_nop 0
	v_pk_add_f32 v[198:199], v[90:91], v[198:199]
	v_mfma_f32_32x32x16_bf16 v[4:19], v[214:217], v[164:167], v[4:19]
	v_exp_f32_e32 v96, v96
	v_exp_f32_e32 v97, v97
	v_exp_f32_e32 v98, v98
	v_exp_f32_e32 v99, v99
	v_pk_add_f32 v[198:199], v[92:93], v[198:199]
	s_nop 0
	v_pk_add_f32 v[198:199], v[94:95], v[198:199]
	s_waitcnt lgkmcnt(2)
	v_mfma_f32_32x32x16_bf16 v[52:67], v[190:193], v[152:155], v[52:67]
	v_exp_f32_e32 v68, v68
	v_exp_f32_e32 v69, v69
	v_exp_f32_e32 v70, v70
	v_exp_f32_e32 v71, v71
	v_pk_add_f32 v[198:199], v[96:97], v[198:199]
	s_nop 0
	v_pk_add_f32 v[198:199], v[98:99], v[198:199]
	v_mfma_f32_32x32x16_bf16 v[36:51], v[190:193], v[140:143], v[36:51]
	v_exp_f32_e32 v72, v72
	v_exp_f32_e32 v73, v73
	v_exp_f32_e32 v74, v74
	v_exp_f32_e32 v75, v75
	v_pk_add_f32 v[190:191], v[68:69], v[198:199]
	s_nop 0
	v_pk_add_f32 v[190:191], v[70:71], v[190:191]
	s_waitcnt lgkmcnt(0)
	v_mfma_f32_32x32x16_bf16 v[20:35], v[194:197], v[152:155], v[20:35]
	v_exp_f32_e32 v76, v76
	v_exp_f32_e32 v77, v77
	v_exp_f32_e32 v78, v78
	v_exp_f32_e32 v79, v79
	v_pk_add_f32 v[190:191], v[72:73], v[190:191]
	s_nop 0
	v_pk_add_f32 v[190:191], v[74:75], v[190:191]
	v_mfma_f32_32x32x16_bf16 v[4:19], v[194:197], v[140:143], v[4:19]
	v_exp_f32_e32 v80, v80
	v_exp_f32_e32 v81, v81
	v_exp_f32_e32 v82, v82
	v_exp_f32_e32 v83, v83
	v_pk_add_f32 v[190:191], v[76:77], v[190:191]
	s_nop 0
	v_pk_add_f32 v[190:191], v[78:79], v[190:191]
	s_nop 0
	v_pk_add_f32 v[190:191], v[80:81], v[190:191]
	s_nop 0
	v_pk_add_f32 v[190:191], v[82:83], v[190:191]
	v_mov_b32_e32 v192, v2
	v_mov_b32_e32 v193, v190
	v_mov_b32_e32 v190, v3
	v_pk_add_f32 v[214:215], v[192:193], v[190:191]
	s_and_b64 vcc, exec, s[14:15]
	s_mov_b64 s[0:1], -1
	s_cbranch_vccz .LBB0_279
	v_cmp_ngt_f32_e32 vcc, s82, v214
	v_cmp_ngt_f32_e64 s[4:5], s82, v215
	s_mov_b32 s14, 0
	s_or_b64 vcc, vcc, s[4:5]
	s_cselect_b64 s[0:1], 0, -1
	s_cbranch_vccz .LBB0_279
	v_mov_b32_e32 v2, v0
	v_mov_b32_e32 v3, v0
	v_mov_b32_e32 v1, v0
	v_mov_b64_e32 v[142:143], v[2:3]
	v_mov_b64_e32 v[166:167], v[2:3]
	v_mov_b64_e32 v[182:183], v[2:3]
	v_mov_b64_e32 v[186:187], v[2:3]
	v_mov_b64_e32 v[154:155], v[2:3]
	v_mov_b64_e32 v[146:147], v[2:3]
	v_mov_b64_e32 v[174:175], v[2:3]
	v_mov_b64_e32 v[178:179], v[2:3]
	s_mov_b32 s14, 41
	v_mov_b64_e32 v[140:141], v[0:1]
	v_mov_b64_e32 v[164:165], v[0:1]
	v_mov_b64_e32 v[180:181], v[0:1]
	v_mov_b64_e32 v[184:185], v[0:1]
	v_mov_b64_e32 v[152:153], v[0:1]
	v_mov_b64_e32 v[144:145], v[0:1]
	v_mov_b64_e32 v[172:173], v[0:1]
	v_mov_b64_e32 v[176:177], v[0:1]
